# combined: conversion gain hoist + GLA pre-pass wait fixes + attention next-tile prefetch kept in flight + MFMA runs 8-byte aligned
# speedup vs baseline: 1.0065x; 1.0002x over previous
; __device__ __forceinline__ void att_unit(LAS unsigned char* lds, const bf16* PROJ, const float* COS, const float* SIN, const float* sinks, bf16* YA, int u) {
;     ...
;     const int wave = __builtin_amdgcn_readfirstlane(tid >> 6), lane = tid & 63, g = lane >> 4, c = lane & 15;
;     v4u qlo, qhi, nlo, nhi; f32x4 qc0, qc1, qs0, qs1, nc0, nc1, ns0, ns1;
;     ...
;     ATT_LOADQ(qlo, qhi, qc0, qc1, qs0, qs1, 0);
;     __syncthreads();
; #pragma unroll 1
;     for (int ti = 0; ti < 3; ++ti) {
;         const int id = 3 * wave + ti, gq = id >> 3, qt = id & 7, hq = kvh * 3 + gq, qi = 16 * qt + c, kb0 = qt >> 1;
;         const size_t t = (size_t)(b * SEQ + 128 * blk + qi);
;         if (ti + 1 < 3) ATT_LOADQ(nlo, nhi, nc0, nc1, ns0, ns1, ti + 1);
;         bf16x8_t qb[2];
;         { const float x1[8] = {bflo(qlo.x), bfhi(qlo.x), bflo(qlo.y), bfhi(qlo.y), bflo(qlo.z), bfhi(qlo.z), bflo(qlo.w), bfhi(qlo.w)};
;           const float x2[8] = {bflo(qhi.x), bfhi(qhi.x), bflo(qhi.y), bfhi(qhi.y), bflo(qhi.z), bfhi(qhi.z), bflo(qhi.w), bfhi(qhi.w)};
;           const float cc[8] = {qc0.x, qc0.y, qc0.z, qc0.w, qc1.x, qc1.y, qc1.z, qc1.w}, ss[8] = {qs0.x, qs0.y, qs0.z, qs0.w, qs1.x, qs1.y, qs1.z, qs1.w};
;           float q1[8], q2[8];
; #pragma unroll
;           for (int j = 0; j < 8; ++j) { q1[j] = (x1[j] * cc[j] - x2[j] * ss[j]) * 0.125f; q2[j] = (x2[j] * cc[j] + x1[j] * ss[j]) * 0.125f; }
;           v4u w1, w2; w1.x = pk2(q1[0], q1[1]); w1.y = pk2(q1[2], q1[3]); w1.z = pk2(q1[4], q1[5]); w1.w = pk2(q1[6], q1[7]);
;           w2.x = pk2(q2[0], q2[1]); w2.y = pk2(q2[2], q2[3]); w2.z = pk2(q2[4], q2[5]); w2.w = pk2(q2[6], q2[7]);
;           qb[0] = __builtin_bit_cast(bf16x8_t, w1); qb[1] = __builtin_bit_cast(bf16x8_t, w2); }
;         bf16x8_t kf[10][2];
; #pragma unroll
;         for (int kt = 0; kt < 10; ++kt)
; #pragma unroll
;             for (int ks = 0; ks < 2; ++ks) kf[kt][ks] = *(const LAS bf16x8_t*)(Ks + (32 * kb0 + 16 * kt + c) * 72 + 32 * ks + 8 * g);
;         __builtin_amdgcn_sched_barrier(0);
;         f32x4 st[10];
; #pragma unroll
;         for (int kt = 0; kt < 10; ++kt) { f32x4 acc = (f32x4){0.f, 0.f, 0.f, 0.f};
; #pragma unroll
;             for (int ks = 0; ks < 2; ++ks) acc = __builtin_amdgcn_mfma_f32_16x16x32_bf16(kf[kt][ks], qb[ks], acc, 0, 0, 0);
;             st[kt] = acc; }
;         v2u vlo[5][4], vhi[5][4];
; #pragma unroll
.LBB0_916:
	s_or_b64 exec, exec, s[2:3]
	v_readfirstlane_b32 s0, v28
	s_ashr_i32 s0, s0, 6
	s_mul_i32 s48, s0, 48
	s_mul_i32 s2, s0, 3
	s_and_b32 s0, s48, 0x70
	v_and_b32_e32 v133, 15, v28
	s_or_b32 s0, s40, s0
	s_mul_i32 s42, s6, 3
	s_lshr_b32 s1, s2, 3
	v_or_b32_e32 v4, s0, v133
	v_mov_b64_e32 v[6:7], s[88:89]
	s_add_i32 s3, s1, s42
	v_mad_i64_i32 v[6:7], s[0:1], v4, s77, v[6:7]
	s_lshl_b32 s0, s3, 6
	v_bfe_u32 v10, v28, 4, 2
	s_ashr_i32 s1, s0, 31
	v_ashrrev_i32_e32 v5, 31, v4
	v_lshl_add_u64 v[6:7], s[0:1], 1, v[6:7]
	v_lshlrev_b32_e32 v2, 4, v10
	v_readlane_b32 s0, v253, 3
	v_readlane_b32 s4, v253, 5
	v_lshl_add_u64 v[6:7], v[6:7], 0, v[2:3]
	v_lshlrev_b64 v[4:5], 7, v[4:5]
	v_readlane_b32 s1, v253, 4
	v_readlane_b32 s5, v253, 6
	global_load_dwordx4 v[36:39], v[6:7], off
	global_load_dwordx4 v[32:35], v[6:7], off offset:64
	v_lshl_add_u64 v[6:7], s[0:1], 0, v[4:5]
	v_lshlrev_b32_e32 v8, 5, v10
	v_mov_b32_e32 v9, v3
	v_lshl_add_u64 v[4:5], s[4:5], 0, v[4:5]
	v_lshl_add_u64 v[6:7], v[6:7], 0, v[8:9]
	v_lshl_add_u64 v[4:5], v[4:5], 0, v[8:9]
	global_load_dwordx4 v[28:31], v[6:7], off offset:16
	global_load_dwordx4 v[44:47], v[6:7], off
	global_load_dwordx4 v[40:43], v[4:5], off offset:16
	global_load_dwordx4 v[48:51], v[4:5], off
	v_and_b32_e32 v6, 64, v223
	v_xor_b32_e32 v5, 16, v223
	v_add_u32_e32 v6, 64, v6
	v_cmp_lt_i32_e32 vcc, v5, v6
	v_lshlrev_b32_e32 v4, 3, v10
	v_add_u32_e32 v136, 0, v2
	v_cndmask_b32_e32 v5, v223, v5, vcc
	v_lshlrev_b32_e32 v137, 2, v5
	v_xor_b32_e32 v5, 32, v223
	v_cmp_lt_i32_e32 vcc, v5, v6
	v_lshl_add_u64 v[128:129], s[0:1], 0, v[8:9]
	v_sub_u32_e32 v2, v136, v4
	v_cndmask_b32_e32 v5, v223, v5, vcc
	s_movk_i32 s0, 0x210
	v_lshl_add_u64 v[130:131], s[4:5], 0, v[8:9]
	v_lshlrev_b32_e32 v132, 2, v10
	s_mov_b32 s45, 0
	v_lshlrev_b32_e32 v138, 2, v5
	v_or_b32_e32 v139, s40, v133
	v_mad_u32_u24 v140, v133, s0, v2
	s_add_i32 s48, s48, 16
	v_lshlrev_b32_e32 v134, 1, v4
	s_waitcnt lgkmcnt(0)
	s_barrier
	s_waitcnt vmcnt(0)
	s_branch .LBB0_918
.LBB0_917:
	v_lshlrev_b32_e32 v53, 16, v37
	v_lshlrev_b32_e32 v52, 16, v36
	v_and_b32_e32 v37, 0xffff0000, v37
	v_and_b32_e32 v36, 0xffff0000, v36
	v_mov_b32_e32 v59, v50
	v_mov_b32_e32 v50, v49
	v_lshlrev_b32_e32 v55, 16, v33
	v_lshlrev_b32_e32 v54, 16, v32
	v_and_b32_e32 v33, 0xffff0000, v33
	v_and_b32_e32 v32, 0xffff0000, v32
	v_mov_b32_e32 v56, v44
	v_mov_b32_e32 v57, v46
	v_mov_b32_e32 v58, v48
	v_mov_b32_e32 v46, v45
	v_pk_mul_f32 v[44:45], v[50:51], v[36:37]
	v_pk_mul_f32 v[48:49], v[58:59], v[54:55]
	v_pk_fma_f32 v[44:45], v[46:47], v[32:33], v[44:45]
	v_pk_mul_f32 v[32:33], v[50:51], v[32:33]
	v_pk_mul_f32 v[60:61], v[58:59], v[52:53]
	v_pk_fma_f32 v[48:49], v[56:57], v[52:53], v[48:49] neg_lo:[0,0,1] neg_hi:[0,0,1]
	v_pk_fma_f32 v[32:33], v[46:47], v[36:37], v[32:33] neg_lo:[0,0,1] neg_hi:[0,0,1]
	v_lshlrev_b32_e32 v37, 16, v39
	v_lshlrev_b32_e32 v36, 16, v38
	v_and_b32_e32 v39, 0xffff0000, v39
	v_and_b32_e32 v38, 0xffff0000, v38
	v_mov_b32_e32 v53, v42
	v_mov_b32_e32 v42, v41
	v_lshlrev_b32_e32 v47, 16, v35
	v_lshlrev_b32_e32 v46, 16, v34
	v_and_b32_e32 v35, 0xffff0000, v35
	v_and_b32_e32 v34, 0xffff0000, v34
	v_mov_b32_e32 v50, v28
	v_mov_b32_e32 v51, v30
	v_mov_b32_e32 v30, v29
	v_pk_mul_f32 v[28:29], v[42:43], v[38:39]
	v_mov_b32_e32 v52, v40
	v_pk_fma_f32 v[28:29], v[30:31], v[34:35], v[28:29]
	v_pk_mul_f32 v[34:35], v[42:43], v[34:35]
	v_pk_mul_f32 v[40:41], v[52:53], v[46:47]
	v_pk_fma_f32 v[30:31], v[30:31], v[38:39], v[34:35] neg_lo:[0,0,1] neg_hi:[0,0,1]
	v_pk_fma_f32 v[60:61], v[56:57], v[54:55], v[60:61]
	v_pk_mul_f32 v[30:31], v[30:31], s[94:95] op_sel_hi:[1,0]
	v_pk_mul_f32 v[48:49], v[48:49], s[94:95] op_sel_hi:[1,0]
	v_pk_mul_f32 v[32:33], v[32:33], s[94:95] op_sel_hi:[1,0]
	v_pk_mul_f32 v[54:55], v[52:53], v[36:37]
	v_pk_fma_f32 v[36:37], v[50:51], v[36:37], v[40:41] neg_lo:[0,0,1] neg_hi:[0,0,1]
	v_bfe_u32 v34, v31, 16, 1
	v_pk_mul_f32 v[36:37], v[36:37], s[94:95] op_sel_hi:[1,0]
	v_bfe_u32 v38, v33, 16, 1
	v_bfe_u32 v39, v32, 16, 1
	v_add3_u32 v31, v31, v34, s81
	v_bfe_u32 v34, v48, 16, 1
	v_pk_fma_f32 v[54:55], v[50:51], v[46:47], v[54:55]
	v_bfe_u32 v35, v30, 16, 1
	v_add3_u32 v32, v32, v39, s81
	v_add3_u32 v33, v33, v38, s81
	v_bfe_u32 v38, v36, 16, 1
	v_bfe_u32 v39, v37, 16, 1
	v_add3_u32 v34, v48, v34, s81
	v_pk_mul_f32 v[54:55], v[54:55], s[94:95] op_sel_hi:[1,0]
	v_add3_u32 v30, v30, v35, s81
	v_bfe_u32 v35, v49, 16, 1
	v_add3_u32 v37, v37, v39, s81
	v_add3_u32 v36, v36, v38, s81
	v_lshrrev_b32_e32 v34, 16, v34
	s_ashr_i32 s0, s2, 3
	s_and_b32 s1, s2, 7
	v_pk_mul_f32 v[64:65], v[60:61], s[94:95] op_sel_hi:[1,0]
	v_pk_mul_f32 v[28:29], v[28:29], s[94:95] op_sel_hi:[1,0]
	v_add3_u32 v35, v49, v35, s81
	v_lshrrev_b32_e32 v36, 16, v36
	v_lshrrev_b32_e32 v37, 16, v37
	v_and_or_b32 v60, v32, s82, v34
	v_bfe_u32 v34, v54, 16, 1
	s_add_i32 s70, s0, s42
	s_lshl_b32 s1, s1, 4
	s_bfe_u32 s0, s2, 0x20001
	v_lshrrev_b32_e32 v35, 16, v35
	v_and_or_b32 v63, v31, s82, v37
	v_and_or_b32 v62, v30, s82, v36
	v_bfe_u32 v30, v29, 16, 1
	v_bfe_u32 v31, v28, 16, 1
	v_add3_u32 v34, v54, v34, s81
	v_or_b32_e32 v2, s1, v133
	s_or_b32 s50, s1, s40
	v_pk_mul_f32 v[44:45], v[44:45], s[94:95] op_sel_hi:[1,0]
	v_and_or_b32 v61, v33, s82, v35
	v_add3_u32 v28, v28, v31, s81
	v_add3_u32 v29, v29, v30, s81
	v_bfe_u32 v30, v64, 16, 1
	v_bfe_u32 v31, v65, 16, 1
	v_bfe_u32 v35, v55, 16, 1
	v_lshrrev_b32_e32 v34, 16, v34
	s_lshl_b32 s1, s0, 5
	v_bfe_u32 v32, v45, 16, 1
	v_bfe_u32 v33, v44, 16, 1
	v_add3_u32 v35, v55, v35, s81
	v_add3_u32 v31, v65, v31, s81
	v_add3_u32 v30, v64, v30, s81
	v_and_or_b32 v66, v28, s82, v34
	v_or_b32_e32 v28, s1, v133
	v_add3_u32 v33, v44, v33, s81
	v_add3_u32 v32, v45, v32, s81
	v_lshrrev_b32_e32 v30, 16, v30
	v_lshrrev_b32_e32 v31, 16, v31
	v_lshrrev_b32_e32 v35, 16, v35
	v_mad_u32_u24 v48, v28, s66, v136
	v_and_or_b32 v67, v29, s82, v35
	v_and_or_b32 v65, v32, s82, v31
	v_and_or_b32 v64, v33, s82, v30
	ds_read_b128 v[28:31], v48
	ds_read_b128 v[32:35], v48 offset:64
	ds_read_b128 v[36:39], v48 offset:2304
	ds_read_b128 v[40:43], v48 offset:2368
	ds_read_b128 v[44:47], v48 offset:4608
	ds_read_b128 v[80:83], v48 offset:4672
	ds_read_b128 v[108:111], v48 offset:6912
	ds_read_b128 v[148:151], v48 offset:6976
	ds_read_b128 v[152:155], v48 offset:9216
	ds_read_b128 v[104:107], v48 offset:9280
	ds_read_b128 v[124:127], v48 offset:11520
	ds_read_b128 v[92:95], v48 offset:11584
	ds_read_b128 v[120:123], v48 offset:13824
	ds_read_b128 v[100:103], v48 offset:13888
	ds_read_b128 v[112:115], v48 offset:16128
	ds_read_b128 v[76:79], v48 offset:16192
	ds_read_b128 v[116:119], v48 offset:18432
	ds_read_b128 v[84:87], v48 offset:18496
	ds_read_b128 v[72:75], v48 offset:20736
	ds_read_b128 v[68:71], v48 offset:20800
	s_ashr_i32 s71, s70, 31
	s_lshl_b64 s[2:3], s[70:71], 2
	s_add_u32 s2, s24, s2
	s_addc_u32 s3, s25, s3
	global_load_dword v135, v3, s[2:3]
	s_waitcnt lgkmcnt(14)
; #define LAS __attribute__((address_space(3)))
; __device__ __forceinline__ void att_unit(LAS unsigned char* lds, const bf16* PROJ, const float* COS, const float* SIN, const float* sinks, bf16* YA, int u) {
;     ...
;         bf16x8_t kf[10][2];
; #pragma unroll
;         for (int kt = 0; kt < 10; ++kt)
; #pragma unroll
;             for (int ks = 0; ks < 2; ++ks) kf[kt][ks] = *(const LAS bf16x8_t*)(Ks + (32 * kb0 + 16 * kt + c) * 72 + 32 * ks + 8 * g);
;         __builtin_amdgcn_sched_barrier(0);
;         f32x4 st[10];
; #pragma unroll
;         for (int kt = 0; kt < 10; ++kt) { f32x4 acc = (f32x4){0.f, 0.f, 0.f, 0.f};
; #pragma unroll
;             for (int ks = 0; ks < 2; ++ks) acc = __builtin_amdgcn_mfma_f32_16x16x32_bf16(kf[kt][ks], qb[ks], acc, 0, 0, 0);
;             st[kt] = acc; }
;         v2u vlo[5][4], vhi[5][4];
; #pragma unroll
;         for (int ks = 0; ks < 5; ++ks)
; #pragma unroll
;             for (int dt = 0; dt < 4; ++dt) { const LAS bf16* vr = VT + (16 * dt + c) * 264 + 32 * (kb0 + ks) + 4 * g; vlo[ks][dt] = *(const LAS v2u*)vr; vhi[ks][dt] = *(const LAS v2u*)(vr + 16); }
;         const float sink = sinks[hq];
;         float m = sink;
; #pragma unroll
;         for (int kt = 0; kt < 10; ++kt)
; #pragma unroll
;             for (int r = 0; r < 4; ++r) { const int kk = 32 * kb0 + 16 * kt + 4 * g + r; const bool ok = (kk >= qi + 1) && (kk <= qi + 128) && (kk >= kk0);
;                 st[kt][r] = ok ? st[kt][r] : -1e30f; m = fmaxf(m, st[kt][r]); }
	v_mfma_f32_16x16x32_bf16 v[28:31], v[28:31], v[60:63], 0
	v_or_b32_e32 v146, s1, v132
	v_or_b32_e32 v156, 1, v146
	v_cmp_gt_u32_e64 s[18:19], v146, v2
	s_waitcnt lgkmcnt(13)
	v_mfma_f32_16x16x32_bf16 v[108:111], v[108:111], v[60:63], 0
	v_cmp_ge_u32_e64 s[28:29], v146, v2
	v_cmp_le_u32_e64 s[30:31], s41, v156
	v_or_b32_e32 v145, 0x80, v2
	v_mfma_f32_16x16x32_bf16 v[96:99], v[32:35], v[64:67], v[28:31]
	v_lshl_add_u32 v32, s0, 6, v140
	v_cmp_le_u32_e64 s[0:1], s41, v146
	s_and_b64 s[0:1], s[18:19], s[0:1]
	v_mfma_f32_16x16x32_bf16 v[28:31], v[36:39], v[60:63], 0
	v_or_b32_e32 v147, 0x82, v146
	s_nop 2
	v_cndmask_b32_e64 v96, v224, v96, s[0:1]
	s_and_b64 s[0:1], s[28:29], s[30:31]
	s_waitcnt lgkmcnt(12)
	v_mfma_f32_16x16x32_bf16 v[108:111], v[148:151], v[64:67], v[108:111]
	v_cndmask_b32_e64 v97, v224, v97, s[0:1]
	v_add_u32_e32 v142, 0x9000, v32
	v_add_u32_e32 v143, 0xb000, v32
	s_waitcnt lgkmcnt(11)
	v_mfma_f32_16x16x32_bf16 v[148:151], v[152:155], v[60:63], 0
	v_or_b32_e32 v152, 2, v146
	v_cmp_gt_u32_e64 s[20:21], v152, v2
	v_cmp_le_u32_e64 s[22:23], s41, v152
	s_waitcnt lgkmcnt(3)
	v_mfma_f32_16x16x32_bf16 v[116:119], v[116:119], v[60:63], 0
	s_and_b64 s[0:1], s[20:21], s[22:23]
	v_cndmask_b32_e64 v98, v224, v98, s[0:1]
	v_add_u32_e32 v144, 0xd000, v32
	v_mfma_f32_16x16x32_bf16 v[124:127], v[124:127], v[60:63], 0
	ds_read2_b64 v[56:59], v142 offset1:4
	ds_read2_b64 v[52:55], v143 offset0:32 offset1:36
	ds_read2_b64 v[48:51], v144 offset0:64 offset1:68
	v_mfma_f32_16x16x32_bf16 v[88:91], v[40:43], v[64:67], v[28:31]
	v_add_u32_e32 v141, 0xf000, v32
	v_mfma_f32_16x16x32_bf16 v[104:107], v[104:107], v[64:67], v[148:151]
	s_nop 2
	v_or_b32_e32 v148, 3, v146
	v_mfma_f32_16x16x32_bf16 v[112:115], v[112:115], v[60:63], 0
	v_cmp_gt_u32_e64 s[4:5], v148, v2
	v_cmp_le_u32_e64 s[8:9], s41, v148
	v_or_b32_e32 v148, 16, v146
	v_mfma_f32_16x16x32_bf16 v[28:31], v[44:47], v[60:63], 0
	v_cmp_gt_u32_e32 vcc, v148, v2
	v_cmp_le_u32_e64 s[2:3], s41, v148
	s_and_b64 vcc, vcc, s[2:3]
	s_waitcnt lgkmcnt(5)
	v_mfma_f32_16x16x32_bf16 v[84:87], v[84:87], v[64:67], v[116:119]
	s_and_b64 s[4:5], s[4:5], s[8:9]
	v_cndmask_b32_e64 v99, v224, v99, s[4:5]
	ds_read2_b64 v[44:47], v141 offset0:96 offset1:100
	ds_read2_b64 v[40:43], v142 offset0:8 offset1:12
	v_mfma_f32_16x16x32_bf16 v[92:95], v[92:95], v[64:67], v[124:127]
	s_nop 2
	v_cndmask_b32_e64 v116, v84, v224, s[18:19]
	v_add_u32_e32 v84, 32, v146
	v_cmp_gt_u32_e64 s[0:1], v84, v2
	v_or_b32_e32 v124, 17, v146
	v_cmp_gt_u32_e64 s[6:7], v124, v2
	v_cmp_le_u32_e64 s[10:11], s41, v124
	v_or_b32_e32 v124, 18, v146
	v_mfma_f32_16x16x32_bf16 v[120:123], v[120:123], v[60:63], 0
	v_cmp_gt_u32_e64 s[12:13], v124, v2
	v_cmp_le_u32_e64 s[14:15], s41, v124
	v_or_b32_e32 v124, 19, v146
	v_mfma_f32_16x16x32_bf16 v[76:79], v[76:79], v[64:67], v[112:115]
	v_cmp_gt_u32_e64 s[16:17], v124, v2
	v_cmp_le_u32_e64 s[18:19], s41, v124
	v_cmp_le_u32_e64 s[4:5], v84, v145
	s_waitcnt lgkmcnt(6)
	v_mfma_f32_16x16x32_bf16 v[60:63], v[72:75], v[60:63], 0
	v_cndmask_b32_e32 v112, v224, v88, vcc
	s_and_b64 vcc, s[6:7], s[10:11]
	v_cndmask_b32_e32 v113, v224, v89, vcc
	v_mfma_f32_16x16x32_bf16 v[80:83], v[80:83], v[64:67], v[28:31]
	s_and_b64 vcc, s[12:13], s[14:15]
	v_cndmask_b32_e32 v114, v224, v90, vcc
	s_and_b64 vcc, s[16:17], s[18:19]
	v_cndmask_b32_e32 v115, v224, v91, vcc
	s_and_b64 s[0:1], s[0:1], s[4:5]
	v_cmp_le_u32_e32 vcc, s41, v84
	v_mfma_f32_16x16x32_bf16 v[100:103], v[100:103], v[64:67], v[120:123]
	s_and_b64 vcc, s[0:1], vcc
	v_cndmask_b32_e32 v117, v224, v80, vcc
	ds_read2_b64 v[36:39], v143 offset0:40 offset1:44
	ds_read2_b64 v[32:35], v144 offset0:72 offset1:76
	ds_read2_b64 v[28:31], v141 offset0:104 offset1:108
	s_waitcnt lgkmcnt(8)
	v_mfma_f32_16x16x32_bf16 v[60:63], v[68:71], v[64:67], v[60:63]
	v_add_u32_e32 v65, 33, v146
	v_cmp_gt_u32_e32 vcc, v65, v2
	v_cmp_le_u32_e64 s[0:1], v65, v145
	s_and_b64 s[0:1], vcc, s[0:1]
	v_cmp_le_u32_e32 vcc, s41, v65
	s_and_b64 vcc, s[0:1], vcc
	v_add_u32_e32 v65, 34, v146
	v_cndmask_b32_e32 v118, v224, v81, vcc
	v_cmp_gt_u32_e32 vcc, v65, v2
	v_cmp_le_u32_e64 s[0:1], v65, v145
	s_and_b64 s[0:1], vcc, s[0:1]
	v_cmp_le_u32_e32 vcc, s41, v65
	s_and_b64 vcc, s[0:1], vcc
	v_add_u32_e32 v65, 35, v146
	v_cndmask_b32_e32 v119, v224, v82, vcc
	v_cmp_gt_u32_e32 vcc, v65, v2
	v_cmp_le_u32_e64 s[0:1], v65, v145
	s_and_b64 s[0:1], vcc, s[0:1]
	v_cmp_le_u32_e32 vcc, s41, v65
	s_and_b64 vcc, s[0:1], vcc
	v_add_u32_e32 v65, 48, v146
	v_cndmask_b32_e32 v120, v224, v83, vcc
	v_cmp_gt_u32_e32 vcc, v65, v2
	v_cmp_le_u32_e64 s[0:1], v65, v145
	s_and_b64 s[0:1], vcc, s[0:1]
	v_cmp_le_u32_e32 vcc, s41, v65
	s_and_b64 vcc, s[0:1], vcc
	v_add_u32_e32 v65, 49, v146
	v_cndmask_b32_e32 v108, v224, v108, vcc
	v_cmp_gt_u32_e32 vcc, v65, v2
	v_cmp_le_u32_e64 s[0:1], v65, v145
	s_and_b64 s[0:1], vcc, s[0:1]
	v_cmp_le_u32_e32 vcc, s41, v65
	s_and_b64 vcc, s[0:1], vcc
	v_add_u32_e32 v65, 50, v146
	v_cndmask_b32_e32 v109, v224, v109, vcc
	v_cmp_gt_u32_e32 vcc, v65, v2
	v_cmp_le_u32_e64 s[0:1], v65, v145
	s_and_b64 s[0:1], vcc, s[0:1]
	v_cmp_le_u32_e32 vcc, s41, v65
	s_and_b64 vcc, s[0:1], vcc
	v_add_u32_e32 v65, 51, v146
	v_cndmask_b32_e32 v110, v224, v110, vcc
	v_cmp_gt_u32_e32 vcc, v65, v2
	v_cmp_le_u32_e64 s[0:1], v65, v145
	s_and_b64 s[0:1], vcc, s[0:1]
	v_cmp_le_u32_e32 vcc, s41, v65
	s_and_b64 vcc, s[0:1], vcc
	v_add_u32_e32 v65, 64, v146
	v_cndmask_b32_e32 v111, v224, v111, vcc
	v_cmp_gt_u32_e32 vcc, v65, v2
	v_cmp_le_u32_e64 s[0:1], v65, v145
	s_and_b64 s[0:1], vcc, s[0:1]
	v_cmp_le_u32_e32 vcc, s41, v65
	s_and_b64 vcc, s[0:1], vcc
	v_add_u32_e32 v65, 0x41, v146
	v_cndmask_b32_e32 v104, v224, v104, vcc
; #define LAS __attribute__((address_space(3)))
; __device__ __forceinline__ void att_unit(LAS unsigned char* lds, const bf16* PROJ, const float* COS, const float* SIN, const float* sinks, bf16* YA, int u) {
;     ...
;             for (int dt = 0; dt < 4; ++dt) { const LAS bf16* vr = VT + (16 * dt + c) * 264 + 32 * (kb0 + ks) + 4 * g; vlo[ks][dt] = *(const LAS v2u*)vr; vhi[ks][dt] = *(const LAS v2u*)(vr + 16); }
;         const float sink = sinks[hq];
;         float m = sink;
; #pragma unroll
;         for (int kt = 0; kt < 10; ++kt)
; #pragma unroll
;             for (int r = 0; r < 4; ++r) { const int kk = 32 * kb0 + 16 * kt + 4 * g + r; const bool ok = (kk >= qi + 1) && (kk <= qi + 128) && (kk >= kk0);
;                 st[kt][r] = ok ? st[kt][r] : -1e30f; m = fmaxf(m, st[kt][r]); }
;         m = fmaxf(m, __shfl_xor(m, 16)); m = fmaxf(m, __shfl_xor(m, 32));
	v_cmp_gt_u32_e32 vcc, v65, v2
	v_cmp_le_u32_e64 s[0:1], v65, v145
	s_and_b64 s[0:1], vcc, s[0:1]
	v_cmp_le_u32_e32 vcc, s41, v65
	s_and_b64 vcc, s[0:1], vcc
	v_add_u32_e32 v65, 0x42, v146
	v_cndmask_b32_e32 v105, v224, v105, vcc
	v_cmp_gt_u32_e32 vcc, v65, v2
	v_cmp_le_u32_e64 s[0:1], v65, v145
	s_and_b64 s[0:1], vcc, s[0:1]
	v_cmp_le_u32_e32 vcc, s41, v65
	s_and_b64 vcc, s[0:1], vcc
	v_add_u32_e32 v65, 0x43, v146
	v_cndmask_b32_e32 v106, v224, v106, vcc
	v_cmp_gt_u32_e32 vcc, v65, v2
	v_cmp_le_u32_e64 s[0:1], v65, v145
	s_and_b64 s[0:1], vcc, s[0:1]
	v_cmp_le_u32_e32 vcc, s41, v65
	s_and_b64 vcc, s[0:1], vcc
	v_add_u32_e32 v65, 0x50, v146
	v_cndmask_b32_e32 v107, v224, v107, vcc
	v_cmp_gt_u32_e32 vcc, v65, v2
	v_cmp_le_u32_e64 s[0:1], v65, v145
	s_and_b64 s[0:1], vcc, s[0:1]
	v_cmp_le_u32_e32 vcc, s41, v65
	s_and_b64 vcc, s[0:1], vcc
	v_add_u32_e32 v65, 0x51, v146
	v_cndmask_b32_e32 v92, v224, v92, vcc
	v_cmp_gt_u32_e32 vcc, v65, v2
	v_cmp_le_u32_e64 s[0:1], v65, v145
	s_and_b64 s[0:1], vcc, s[0:1]
	v_cmp_le_u32_e32 vcc, s41, v65
	s_and_b64 vcc, s[0:1], vcc
	v_add_u32_e32 v65, 0x52, v146
	v_cndmask_b32_e32 v93, v224, v93, vcc
	v_cmp_gt_u32_e32 vcc, v65, v2
	v_cmp_le_u32_e64 s[0:1], v65, v145
	s_and_b64 s[0:1], vcc, s[0:1]
	v_cmp_le_u32_e32 vcc, s41, v65
	s_and_b64 vcc, s[0:1], vcc
	v_add_u32_e32 v65, 0x53, v146
	v_cndmask_b32_e32 v94, v224, v94, vcc
	v_cmp_gt_u32_e32 vcc, v65, v2
	v_cmp_le_u32_e64 s[0:1], v65, v145
	s_and_b64 s[0:1], vcc, s[0:1]
	v_cmp_le_u32_e32 vcc, s41, v65
	s_and_b64 vcc, s[0:1], vcc
	v_add_u32_e32 v65, 0x60, v146
	v_cndmask_b32_e32 v95, v224, v95, vcc
	v_cmp_gt_u32_e32 vcc, v65, v2
	v_cmp_le_u32_e64 s[0:1], v65, v145
	s_and_b64 s[0:1], vcc, s[0:1]
	v_cmp_le_u32_e32 vcc, s41, v65
	s_and_b64 vcc, s[0:1], vcc
	v_add_u32_e32 v65, 0x61, v146
	v_cndmask_b32_e32 v100, v224, v100, vcc
	v_cmp_gt_u32_e32 vcc, v65, v2
	v_cmp_le_u32_e64 s[0:1], v65, v145
	s_and_b64 s[0:1], vcc, s[0:1]
	v_cmp_le_u32_e32 vcc, s41, v65
	s_and_b64 vcc, s[0:1], vcc
	v_add_u32_e32 v65, 0x62, v146
	v_cndmask_b32_e32 v101, v224, v101, vcc
	v_cmp_gt_u32_e32 vcc, v65, v2
	v_cmp_le_u32_e64 s[0:1], v65, v145
	s_and_b64 s[0:1], vcc, s[0:1]
	v_cmp_le_u32_e32 vcc, s41, v65
	s_and_b64 vcc, s[0:1], vcc
	v_add_u32_e32 v65, 0x63, v146
	v_cndmask_b32_e32 v102, v224, v102, vcc
	v_cmp_gt_u32_e32 vcc, v65, v2
	v_cmp_le_u32_e64 s[0:1], v65, v145
	s_and_b64 s[0:1], vcc, s[0:1]
	v_cmp_le_u32_e32 vcc, s41, v65
	s_and_b64 vcc, s[0:1], vcc
	v_add_u32_e32 v65, 0x70, v146
	v_cndmask_b32_e32 v103, v224, v103, vcc
	v_cmp_gt_u32_e32 vcc, v65, v2
	v_cmp_le_u32_e64 s[0:1], v65, v145
	s_and_b64 s[0:1], vcc, s[0:1]
	v_cmp_le_u32_e32 vcc, s41, v65
	s_and_b64 vcc, s[0:1], vcc
	v_add_u32_e32 v65, 0x71, v146
	s_waitcnt vmcnt(0)
	v_max3_f32 v64, v135, v96, v97
	v_cndmask_b32_e32 v121, v224, v76, vcc
	v_cmp_gt_u32_e32 vcc, v65, v2
	v_cmp_le_u32_e64 s[0:1], v65, v145
	v_max3_f32 v64, v64, v98, v99
	s_and_b64 s[0:1], vcc, s[0:1]
	v_cmp_le_u32_e32 vcc, s41, v65
	v_max3_f32 v64, v64, v112, v113
	s_and_b64 vcc, s[0:1], vcc
	v_add_u32_e32 v65, 0x72, v146
	v_max3_f32 v64, v64, v114, v115
	v_cndmask_b32_e32 v122, v224, v77, vcc
	v_cmp_gt_u32_e32 vcc, v65, v2
	v_cmp_le_u32_e64 s[0:1], v65, v145
	v_max3_f32 v64, v64, v117, v118
	s_and_b64 s[0:1], vcc, s[0:1]
	v_cmp_le_u32_e32 vcc, s41, v65
	v_max3_f32 v64, v64, v119, v120
	s_and_b64 vcc, s[0:1], vcc
	v_add_u32_e32 v65, 0x73, v146
	v_max3_f32 v64, v64, v108, v109
	v_cndmask_b32_e32 v123, v224, v78, vcc
	v_cmp_gt_u32_e32 vcc, v65, v2
	v_cmp_le_u32_e64 s[0:1], v65, v145
	v_max3_f32 v64, v64, v110, v111
	s_and_b64 s[0:1], vcc, s[0:1]
	v_cmp_le_u32_e32 vcc, s41, v65
	v_max3_f32 v64, v64, v104, v105
	s_and_b64 vcc, s[0:1], vcc
	v_max3_f32 v64, v64, v106, v107
	v_cndmask_b32_e32 v124, v224, v79, vcc
	v_cmp_le_u32_e32 vcc, v147, v145
	v_or_b32_e32 v65, 0x83, v146
	v_max3_f32 v64, v64, v92, v93
	v_cndmask_b32_e32 v125, v224, v86, vcc
	v_or_b32_e32 v66, 0x81, v146
	v_cmp_le_u32_e32 vcc, v65, v145
	v_max3_f32 v64, v64, v94, v95
	v_or_b32_e32 v65, 0x92, v146
	v_cndmask_b32_e32 v126, v224, v87, vcc
	v_cmp_le_u32_e32 vcc, v66, v145
	v_max3_f32 v64, v64, v100, v101
	v_or_b32_e32 v66, 0x90, v146
	v_cndmask_b32_e32 v127, v224, v85, vcc
	v_cmp_le_u32_e32 vcc, v65, v145
	v_max3_f32 v64, v64, v102, v103
	v_max3_f32 v64, v64, v121, v122
	v_cndmask_b32_e32 v147, v224, v62, vcc
	v_cmp_le_u32_e32 vcc, v66, v145
	v_max3_f32 v64, v64, v123, v124
	v_or_b32_e32 v62, 0x91, v146
	v_cndmask_b32_e32 v148, v224, v60, vcc
	v_or_b32_e32 v60, 0x93, v146
	v_cmp_le_u32_e32 vcc, v60, v145
	v_max3_f32 v64, v64, v116, v127
	v_max3_f32 v64, v64, v125, v126
	v_cndmask_b32_e32 v146, v224, v63, vcc
	v_cmp_le_u32_e32 vcc, v62, v145
	ds_read2_b64 v[88:91], v142 offset0:16 offset1:20
	ds_read2_b64 v[84:87], v143 offset0:48 offset1:52
	ds_read2_b64 v[80:83], v144 offset0:80 offset1:84
	ds_read2_b64 v[76:79], v141 offset0:112 offset1:116
	v_cndmask_b32_e32 v145, v224, v61, vcc
	v_max3_f32 v60, v64, v148, v145
	v_max3_f32 v60, v60, v147, v146
	ds_bpermute_b32 v61, v137, v60
	v_cmp_lt_f32_e32 vcc, s80, v96
	v_lshlrev_b32_e32 v2, 7, v2
	v_and_b32_e32 v2, 0x1f80, v2
	s_mov_b32 s2, s49
	s_waitcnt lgkmcnt(0)
	v_max_f32_e32 v61, v61, v61
	v_max_f32_e32 v149, v60, v61
	ds_bpermute_b32 v150, v138, v149
	ds_read2_b64 v[72:75], v142 offset0:24 offset1:28
	ds_read2_b64 v[68:71], v143 offset0:56 offset1:60
	ds_read2_b64 v[64:67], v144 offset0:88 offset1:92
	ds_read2_b64 v[60:63], v141 offset0:120 offset1:124
	s_waitcnt lgkmcnt(4)
; __device__ __forceinline__ void att_unit(LAS unsigned char* lds, const bf16* PROJ, const float* COS, const float* SIN, const float* sinks, bf16* YA, int u) {
;     ...
;         float l = 0.f;
; #pragma unroll
;         for (int kt = 0; kt < 10; ++kt)
; #pragma unroll
;             for (int r = 0; r < 4; ++r) { const float p = (st[kt][r] > -1e29f) ? __expf(st[kt][r] - m) : 0.f; st[kt][r] = p; l += p; }
;         l += __shfl_xor(l, 16); l += __shfl_xor(l, 32);
	v_max_f32_e32 v150, v150, v150
	v_max_f32_e32 v149, v149, v150
	v_sub_f32_e32 v150, v96, v149
	v_mul_f32_e32 v150, 0x3fb8aa3b, v150
	v_sub_f32_e32 v151, v97, v149
	v_exp_f32_e32 v150, v150
	v_mul_f32_e32 v151, 0x3fb8aa3b, v151
	v_exp_f32_e32 v151, v151
	v_sub_f32_e32 v152, v99, v149
	v_cndmask_b32_e32 v96, 0, v150, vcc
	v_cmp_lt_f32_e32 vcc, s80, v97
	v_mul_f32_e32 v152, 0x3fb8aa3b, v152
	v_exp_f32_e32 v152, v152
	v_cndmask_b32_e32 v97, 0, v151, vcc
	v_sub_f32_e32 v151, v98, v149
	v_mul_f32_e32 v151, 0x3fb8aa3b, v151
	v_exp_f32_e32 v151, v151
	v_cmp_lt_f32_e32 vcc, s80, v98
	v_add_f32_e32 v150, 0, v96
	v_add_f32_e32 v150, v97, v150
	v_cndmask_b32_e32 v98, 0, v151, vcc
	v_sub_f32_e32 v151, v112, v149
	v_mul_f32_e32 v151, 0x3fb8aa3b, v151
	v_exp_f32_e32 v151, v151
	v_cmp_lt_f32_e32 vcc, s80, v99
	v_add_f32_e32 v150, v98, v150
	v_sub_f32_e32 v156, v126, v149
	v_cndmask_b32_e32 v99, 0, v152, vcc
	v_sub_f32_e32 v152, v113, v149
	v_cmp_lt_f32_e32 vcc, s80, v112
	v_mul_f32_e32 v152, 0x3fb8aa3b, v152
	v_exp_f32_e32 v152, v152
	v_cndmask_b32_e32 v112, 0, v151, vcc
	v_sub_f32_e32 v151, v114, v149
	v_mul_f32_e32 v151, 0x3fb8aa3b, v151
	v_exp_f32_e32 v151, v151
	v_cmp_lt_f32_e32 vcc, s80, v113
	v_add_f32_e32 v150, v99, v150
	v_add_f32_e32 v150, v112, v150
	v_cndmask_b32_e32 v113, 0, v152, vcc
	v_sub_f32_e32 v152, v115, v149
	v_cmp_lt_f32_e32 vcc, s80, v114
	v_mul_f32_e32 v152, 0x3fb8aa3b, v152
	v_exp_f32_e32 v152, v152
	v_cndmask_b32_e32 v114, 0, v151, vcc
	v_sub_f32_e32 v151, v117, v149
	v_mul_f32_e32 v151, 0x3fb8aa3b, v151
	v_exp_f32_e32 v151, v151
	v_cmp_lt_f32_e32 vcc, s80, v115
	v_add_f32_e32 v150, v113, v150
	v_add_f32_e32 v150, v114, v150
	v_cndmask_b32_e32 v115, 0, v152, vcc
	v_sub_f32_e32 v152, v118, v149
	v_cmp_lt_f32_e32 vcc, s80, v117
	v_mul_f32_e32 v152, 0x3fb8aa3b, v152
	v_exp_f32_e32 v152, v152
	v_cndmask_b32_e32 v117, 0, v151, vcc
	v_sub_f32_e32 v151, v119, v149
	v_mul_f32_e32 v151, 0x3fb8aa3b, v151
	v_exp_f32_e32 v151, v151
	v_cmp_lt_f32_e32 vcc, s80, v118
	v_add_f32_e32 v150, v115, v150
	v_add_f32_e32 v150, v117, v150
	v_cndmask_b32_e32 v118, 0, v152, vcc
	v_sub_f32_e32 v152, v120, v149
	v_cmp_lt_f32_e32 vcc, s80, v119
	v_mul_f32_e32 v152, 0x3fb8aa3b, v152
	v_exp_f32_e32 v152, v152
	v_cndmask_b32_e32 v119, 0, v151, vcc
	v_sub_f32_e32 v151, v108, v149
	v_mul_f32_e32 v151, 0x3fb8aa3b, v151
	v_exp_f32_e32 v151, v151
	v_cmp_lt_f32_e32 vcc, s80, v120
	v_add_f32_e32 v150, v118, v150
	v_add_f32_e32 v150, v119, v150
	v_cndmask_b32_e32 v120, 0, v152, vcc
	v_sub_f32_e32 v152, v109, v149
	v_cmp_lt_f32_e32 vcc, s80, v108
	v_mul_f32_e32 v152, 0x3fb8aa3b, v152
	v_exp_f32_e32 v152, v152
	v_cndmask_b32_e32 v108, 0, v151, vcc
	v_sub_f32_e32 v151, v110, v149
	v_mul_f32_e32 v151, 0x3fb8aa3b, v151
	v_exp_f32_e32 v151, v151
	v_cmp_lt_f32_e32 vcc, s80, v109
	v_add_f32_e32 v150, v120, v150
	v_add_f32_e32 v150, v108, v150
	v_cndmask_b32_e32 v109, 0, v152, vcc
	v_sub_f32_e32 v152, v111, v149
	v_cmp_lt_f32_e32 vcc, s80, v110
	v_mul_f32_e32 v152, 0x3fb8aa3b, v152
	v_exp_f32_e32 v152, v152
	v_cndmask_b32_e32 v110, 0, v151, vcc
	v_sub_f32_e32 v151, v104, v149
	v_mul_f32_e32 v151, 0x3fb8aa3b, v151
	v_exp_f32_e32 v151, v151
	v_cmp_lt_f32_e32 vcc, s80, v111
	v_add_f32_e32 v150, v109, v150
	v_add_f32_e32 v150, v110, v150
	v_cndmask_b32_e32 v111, 0, v152, vcc
	v_sub_f32_e32 v152, v105, v149
	v_cmp_lt_f32_e32 vcc, s80, v104
	v_mul_f32_e32 v152, 0x3fb8aa3b, v152
	v_exp_f32_e32 v152, v152
	v_cndmask_b32_e32 v104, 0, v151, vcc
	v_sub_f32_e32 v151, v106, v149
	v_mul_f32_e32 v151, 0x3fb8aa3b, v151
	v_exp_f32_e32 v151, v151
	v_cmp_lt_f32_e32 vcc, s80, v105
	v_add_f32_e32 v150, v111, v150
	v_add_f32_e32 v150, v104, v150
	v_cndmask_b32_e32 v105, 0, v152, vcc
	v_sub_f32_e32 v152, v107, v149
	v_cmp_lt_f32_e32 vcc, s80, v106
	v_mul_f32_e32 v152, 0x3fb8aa3b, v152
	v_exp_f32_e32 v152, v152
	v_cndmask_b32_e32 v106, 0, v151, vcc
	v_sub_f32_e32 v151, v92, v149
	v_mul_f32_e32 v151, 0x3fb8aa3b, v151
	v_exp_f32_e32 v151, v151
	v_cmp_lt_f32_e32 vcc, s80, v107
	v_add_f32_e32 v150, v105, v150
	v_add_f32_e32 v150, v106, v150
	v_cndmask_b32_e32 v107, 0, v152, vcc
	v_sub_f32_e32 v152, v93, v149
	v_cmp_lt_f32_e32 vcc, s80, v92
	v_mul_f32_e32 v152, 0x3fb8aa3b, v152
	v_exp_f32_e32 v152, v152
	v_cndmask_b32_e32 v151, 0, v151, vcc
	v_cmp_lt_f32_e32 vcc, s80, v93
	v_sub_f32_e32 v93, v94, v149
	v_mul_f32_e32 v93, 0x3fb8aa3b, v93
	v_exp_f32_e32 v93, v93
	v_add_f32_e32 v150, v107, v150
	v_add_f32_e32 v92, v151, v150
	v_cndmask_b32_e32 v150, 0, v152, vcc
	v_sub_f32_e32 v152, v95, v149
	v_cmp_lt_f32_e32 vcc, s80, v94
	v_mul_f32_e32 v152, 0x3fb8aa3b, v152
	v_exp_f32_e32 v152, v152
	v_cndmask_b32_e32 v153, 0, v93, vcc
	v_sub_f32_e32 v93, v100, v149
	v_mul_f32_e32 v93, 0x3fb8aa3b, v93
	v_sub_f32_e32 v94, v101, v149
	v_exp_f32_e32 v93, v93
	v_mul_f32_e32 v94, 0x3fb8aa3b, v94
	v_exp_f32_e32 v94, v94
	v_cmp_lt_f32_e32 vcc, s80, v95
	v_add_f32_e32 v92, v150, v92
	v_add_f32_e32 v92, v153, v92
	v_cndmask_b32_e32 v152, 0, v152, vcc
	v_cmp_lt_f32_e32 vcc, s80, v100
	v_add_f32_e32 v92, v152, v92
	v_bfe_u32 v95, v113, 16, 1
	v_cndmask_b32_e32 v100, 0, v93, vcc
	v_cmp_lt_f32_e32 vcc, s80, v101
	v_sub_f32_e32 v93, v102, v149
	v_mul_f32_e32 v93, 0x3fb8aa3b, v93
	v_cndmask_b32_e32 v101, 0, v94, vcc
	v_sub_f32_e32 v94, v103, v149
	v_exp_f32_e32 v93, v93
	v_mul_f32_e32 v94, 0x3fb8aa3b, v94
	v_exp_f32_e32 v94, v94
	v_cmp_lt_f32_e32 vcc, s80, v102
	v_add_f32_e32 v92, v100, v92
	v_add_f32_e32 v92, v101, v92
	v_cndmask_b32_e32 v102, 0, v93, vcc
	v_cmp_lt_f32_e32 vcc, s80, v103
	v_sub_f32_e32 v93, v121, v149
	v_mul_f32_e32 v93, 0x3fb8aa3b, v93
	v_cndmask_b32_e32 v103, 0, v94, vcc
	v_sub_f32_e32 v94, v122, v149
; __device__ __forceinline__ unsigned pk2(float lo, float hi) { return f2bf(lo) | (f2bf(hi) << 16); }
; __device__ __forceinline__ void att_unit(LAS unsigned char* lds, const bf16* PROJ, const float* COS, const float* SIN, const float* sinks, bf16* YA, int u) {
;     ...
;             for (int r = 0; r < 4; ++r) { const float p = (st[kt][r] > -1e29f) ? __expf(st[kt][r] - m) : 0.f; st[kt][r] = p; l += p; }
;         l += __shfl_xor(l, 16); l += __shfl_xor(l, 32);
;         l += __expf(sink - m);
;         f32x4 o[4];
; #pragma unroll
;         for (int dt = 0; dt < 4; ++dt) o[dt] = (f32x4){0.f, 0.f, 0.f, 0.f};
; #pragma unroll
;         for (int ks = 0; ks < 5; ++ks) { v4u pw; pw.x = pk2(st[2 * ks][0], st[2 * ks][1]); pw.y = pk2(st[2 * ks][2], st[2 * ks][3]); pw.z = pk2(st[2 * ks + 1][0], st[2 * ks + 1][1]); pw.w = pk2(st[2 * ks + 1][2], st[2 * ks + 1][3]);
;             const bf16x8_t pb = __builtin_bit_cast(bf16x8_t, pw);
; #pragma unroll
;             for (int dt = 0; dt < 4; ++dt) { const v4u aw = (v4u){vlo[ks][dt].x, vlo[ks][dt].y, vhi[ks][dt].x, vhi[ks][dt].y};
;                 o[dt] = __builtin_amdgcn_mfma_f32_16x16x32_bf16(__builtin_bit_cast(bf16x8_t, aw), pb, o[dt], 0, 0, 0); } }
	v_exp_f32_e32 v93, v93
	v_mul_f32_e32 v94, 0x3fb8aa3b, v94
	v_exp_f32_e32 v94, v94
	v_cmp_lt_f32_e32 vcc, s80, v121
	v_add_f32_e32 v92, v102, v92
	v_add_f32_e32 v92, v103, v92
	v_cndmask_b32_e32 v121, 0, v93, vcc
	v_cmp_lt_f32_e32 vcc, s80, v122
	v_sub_f32_e32 v93, v123, v149
	v_mul_f32_e32 v93, 0x3fb8aa3b, v93
	v_cndmask_b32_e32 v122, 0, v94, vcc
	v_sub_f32_e32 v94, v124, v149
	v_exp_f32_e32 v93, v93
	v_mul_f32_e32 v94, 0x3fb8aa3b, v94
	v_exp_f32_e32 v94, v94
	v_cmp_lt_f32_e32 vcc, s80, v123
	v_add_f32_e32 v92, v121, v92
	v_add_f32_e32 v92, v122, v92
	v_cndmask_b32_e32 v123, 0, v93, vcc
	v_cmp_lt_f32_e32 vcc, s80, v124
	v_sub_f32_e32 v93, v116, v149
	v_mul_f32_e32 v93, 0x3fb8aa3b, v93
	v_cndmask_b32_e32 v124, 0, v94, vcc
	v_sub_f32_e32 v94, v125, v149
	v_mul_f32_e32 v94, 0x3fb8aa3b, v94
	v_exp_f32_e32 v94, v94
	v_exp_f32_e32 v93, v93
	v_cmp_lt_f32_e32 vcc, s80, v125
	v_add_f32_e32 v92, v123, v92
	v_add_f32_e32 v92, v124, v92
	v_cndmask_b32_e32 v125, 0, v94, vcc
	v_cmp_lt_f32_e32 vcc, s80, v116
	v_bfe_u32 v94, v99, 16, 1
	v_add3_u32 v94, v99, v94, s81
	v_cndmask_b32_e32 v116, 0, v93, vcc
	v_add_f32_e32 v154, v116, v92
	v_sub_f32_e32 v92, v127, v149
	v_mul_f32_e32 v155, 0x3fb8aa3b, v92
	v_bfe_u32 v92, v96, 16, 1
	v_add3_u32 v92, v96, v92, s81
	v_bfe_u32 v93, v97, 16, 1
	v_lshrrev_b32_e32 v92, 16, v92
	v_add3_u32 v93, v97, v93, s81
	v_and_or_b32 v92, v93, s82, v92
	v_bfe_u32 v93, v98, 16, 1
	v_add3_u32 v93, v98, v93, s81
	v_lshrrev_b32_e32 v93, 16, v93
	v_and_or_b32 v93, v94, s82, v93
	v_bfe_u32 v94, v112, 16, 1
	v_add3_u32 v94, v112, v94, s81
	v_lshrrev_b32_e32 v94, 16, v94
	v_add3_u32 v95, v113, v95, s81
	v_and_or_b32 v94, v95, s82, v94
	v_bfe_u32 v95, v114, 16, 1
	v_add3_u32 v95, v114, v95, s81
	v_bfe_u32 v96, v115, 16, 1
	v_lshrrev_b32_e32 v95, 16, v95
	v_add3_u32 v96, v115, v96, s81
	v_and_or_b32 v95, v96, s82, v95
	v_bfe_u32 v99, v111, 16, 1
	v_add3_u32 v99, v111, v99, s81
	v_mfma_f32_16x16x32_bf16 v[56:59], v[56:59], v[92:95], 0
	v_mul_f32_e32 v96, 0x3fb8aa3b, v156
	v_exp_f32_e32 v96, v96
	v_exp_f32_e32 v97, v155
	v_mfma_f32_16x16x32_bf16 v[52:55], v[52:55], v[92:95], 0
	v_cmp_lt_f32_e32 vcc, s80, v126
	v_mfma_f32_16x16x32_bf16 v[48:51], v[48:51], v[92:95], 0
	s_nop 0
	v_cndmask_b32_e32 v96, 0, v96, vcc
	v_cmp_lt_f32_e32 vcc, s80, v127
	v_mfma_f32_16x16x32_bf16 v[44:47], v[44:47], v[92:95], 0
	v_bfe_u32 v92, v117, 16, 1
	v_add3_u32 v92, v117, v92, s81
	v_bfe_u32 v93, v118, 16, 1
	v_lshrrev_b32_e32 v92, 16, v92
	v_add3_u32 v93, v118, v93, s81
	v_and_or_b32 v92, v93, s82, v92
	v_bfe_u32 v93, v119, 16, 1
	v_add3_u32 v93, v119, v93, s81
	v_bfe_u32 v94, v120, 16, 1
	v_lshrrev_b32_e32 v93, 16, v93
	v_add3_u32 v94, v120, v94, s81
	v_and_or_b32 v93, v94, s82, v93
	v_bfe_u32 v94, v108, 16, 1
	v_add3_u32 v94, v108, v94, s81
	v_bfe_u32 v95, v109, 16, 1
	v_lshrrev_b32_e32 v94, 16, v94
	v_add3_u32 v95, v109, v95, s81
	v_and_or_b32 v94, v95, s82, v94
	v_bfe_u32 v95, v110, 16, 1
	v_add3_u32 v95, v110, v95, s81
	v_lshrrev_b32_e32 v95, 16, v95
	v_and_or_b32 v95, v99, s82, v95
	v_cndmask_b32_e32 v97, 0, v97, vcc
	v_cmp_lt_f32_e32 vcc, s80, v147
	v_mfma_f32_16x16x32_bf16 v[28:31], v[28:31], v[92:95], v[44:47]
	v_add_f32_e32 v98, v97, v154
	v_add_f32_e32 v98, v125, v98
	v_add_f32_e32 v98, v96, v98
	v_bfe_u32 v44, v104, 16, 1
	v_add3_u32 v44, v104, v44, s81
	v_bfe_u32 v45, v105, 16, 1
	v_lshrrev_b32_e32 v44, 16, v44
	v_add3_u32 v45, v105, v45, s81
	v_and_or_b32 v44, v45, s82, v44
	v_bfe_u32 v45, v106, 16, 1
	v_add3_u32 v45, v106, v45, s81
	v_bfe_u32 v46, v107, 16, 1
	v_lshrrev_b32_e32 v45, 16, v45
	v_add3_u32 v46, v107, v46, s81
	v_and_or_b32 v45, v46, s82, v45
	v_bfe_u32 v46, v151, 16, 1
	v_add3_u32 v46, v151, v46, s81
	v_bfe_u32 v47, v150, 16, 1
	v_lshrrev_b32_e32 v46, 16, v46
	v_add3_u32 v47, v150, v47, s81
	v_mfma_f32_16x16x32_bf16 v[40:43], v[40:43], v[92:95], v[56:59]
	v_and_or_b32 v46, v47, s82, v46
	v_bfe_u32 v47, v153, 16, 1
	v_add3_u32 v47, v153, v47, s81
	v_mfma_f32_16x16x32_bf16 v[36:39], v[36:39], v[92:95], v[52:55]
	v_lshrrev_b32_e32 v47, 16, v47
	v_sub_f32_e32 v57, v147, v149
	v_sub_f32_e32 v56, v148, v149
	v_mfma_f32_16x16x32_bf16 v[32:35], v[32:35], v[92:95], v[48:51]
	v_mul_f32_e32 v52, 0x3fb8aa3b, v57
	v_mul_f32_e32 v56, 0x3fb8aa3b, v56
	v_exp_f32_e32 v52, v52
	v_bfe_u32 v48, v152, 16, 1
	v_add3_u32 v48, v152, v48, s81
	v_and_or_b32 v47, v48, s82, v47
	v_sub_f32_e32 v50, v146, v149
	v_exp_f32_e32 v53, v56
	v_mfma_f32_16x16x32_bf16 v[40:43], v[88:91], v[44:47], v[40:43]
	v_mul_f32_e32 v50, 0x3fb8aa3b, v50
	v_exp_f32_e32 v50, v50
	v_sub_f32_e32 v49, v145, v149
	v_mfma_f32_16x16x32_bf16 v[36:39], v[84:87], v[44:47], v[36:39]
	v_cndmask_b32_e32 v99, 0, v52, vcc
	v_cmp_lt_f32_e32 vcc, s80, v148
	v_mul_f32_e32 v49, 0x3fb8aa3b, v49
	v_mfma_f32_16x16x32_bf16 v[32:35], v[80:83], v[44:47], v[32:35]
	v_cndmask_b32_e32 v108, 0, v53, vcc
	v_exp_f32_e32 v49, v49
	v_cmp_lt_f32_e32 vcc, s80, v146
	v_mfma_f32_16x16x32_bf16 v[28:31], v[76:79], v[44:47], v[28:31]
	v_bfe_u32 v44, v100, 16, 1
	v_add3_u32 v44, v100, v44, s81
	v_bfe_u32 v45, v101, 16, 1
	v_lshrrev_b32_e32 v44, 16, v44
	v_add3_u32 v45, v101, v45, s81
	v_and_or_b32 v44, v45, s82, v44
	v_bfe_u32 v45, v102, 16, 1
	v_add3_u32 v45, v102, v45, s81
	v_bfe_u32 v46, v103, 16, 1
	v_lshrrev_b32_e32 v45, 16, v45
	v_add3_u32 v46, v103, v46, s81
	v_and_or_b32 v45, v46, s82, v45
	v_bfe_u32 v46, v121, 16, 1
	v_add3_u32 v46, v121, v46, s81
	v_bfe_u32 v47, v122, 16, 1
	v_lshrrev_b32_e32 v46, 16, v46
	v_add3_u32 v47, v122, v47, s81
	v_and_or_b32 v46, v47, s82, v46
	v_bfe_u32 v47, v123, 16, 1
	v_cndmask_b32_e32 v80, 0, v50, vcc
	v_add3_u32 v47, v123, v47, s81
	v_bfe_u32 v50, v124, 16, 1
	v_lshrrev_b32_e32 v47, 16, v47
	v_add3_u32 v50, v124, v50, s81
	v_and_or_b32 v47, v50, s82, v47
	v_cmp_lt_f32_e32 vcc, s80, v145
	v_add_f32_e32 v48, v108, v98
	s_waitcnt lgkmcnt(3)
; __device__ __forceinline__ unsigned pk2(float lo, float hi) { return f2bf(lo) | (f2bf(hi) << 16); }
; __device__ __forceinline__ void att_unit(LAS unsigned char* lds, const bf16* PROJ, const float* COS, const float* SIN, const float* sinks, bf16* YA, int u) {
;     ...
;         l += __shfl_xor(l, 16); l += __shfl_xor(l, 32);
;         l += __expf(sink - m);
;         f32x4 o[4];
; #pragma unroll
;         for (int dt = 0; dt < 4; ++dt) o[dt] = (f32x4){0.f, 0.f, 0.f, 0.f};
; #pragma unroll
;         for (int ks = 0; ks < 5; ++ks) { v4u pw; pw.x = pk2(st[2 * ks][0], st[2 * ks][1]); pw.y = pk2(st[2 * ks][2], st[2 * ks][3]); pw.z = pk2(st[2 * ks + 1][0], st[2 * ks + 1][1]); pw.w = pk2(st[2 * ks + 1][2], st[2 * ks + 1][3]);
;             const bf16x8_t pb = __builtin_bit_cast(bf16x8_t, pw);
; #pragma unroll
;             for (int dt = 0; dt < 4; ++dt) { const v4u aw = (v4u){vlo[ks][dt].x, vlo[ks][dt].y, vhi[ks][dt].x, vhi[ks][dt].y};
;                 o[dt] = __builtin_amdgcn_mfma_f32_16x16x32_bf16(__builtin_bit_cast(bf16x8_t, aw), pb, o[dt], 0, 0, 0); } }
;         const float inv = 1.0f / l;
	v_mfma_f32_16x16x32_bf16 v[40:43], v[72:75], v[44:47], v[40:43]
	v_cndmask_b32_e32 v72, 0, v49, vcc
	v_add_f32_e32 v48, v72, v48
	v_add_f32_e32 v48, v99, v48
	s_waitcnt lgkmcnt(2)
	v_mfma_f32_16x16x32_bf16 v[36:39], v[68:71], v[44:47], v[36:39]
	v_add_f32_e32 v68, v80, v48
	ds_read2_b64 v[48:51], v142 offset0:32 offset1:36
	ds_bpermute_b32 v69, v137, v68
	s_waitcnt lgkmcnt(3)
	v_mfma_f32_16x16x32_bf16 v[32:35], v[64:67], v[44:47], v[32:35]
	ds_read2_b64 v[52:55], v143 offset0:64 offset1:68
	ds_read2_b64 v[56:59], v144 offset0:96 offset1:100
	s_waitcnt lgkmcnt(2)
	v_add_f32_e32 v64, v68, v69
	v_mfma_f32_16x16x32_bf16 v[28:31], v[60:63], v[44:47], v[28:31]
	v_bfe_u32 v46, v96, 16, 1
	v_bfe_u32 v47, v97, 16, 1
	v_add3_u32 v60, v97, v47, s81
	v_add3_u32 v61, v96, v46, s81
	v_bfe_u32 v46, v116, 16, 1
	v_bfe_u32 v47, v125, 16, 1
	v_bfe_u32 v62, v108, 16, 1
	v_bfe_u32 v63, v99, 16, 1
	v_bfe_u32 v44, v80, 16, 1
	v_bfe_u32 v45, v72, 16, 1
	v_add3_u32 v63, v99, v63, s81
	v_add3_u32 v62, v108, v62, s81
	v_add3_u32 v47, v125, v47, s81
	v_add3_u32 v46, v116, v46, s81
	v_add3_u32 v45, v72, v45, s81
	v_add3_u32 v44, v80, v44, s81
	v_lshrrev_b32_e32 v65, 16, v46
	v_lshrrev_b32_e32 v66, 16, v47
	v_lshrrev_b32_e32 v46, 16, v62
	v_lshrrev_b32_e32 v47, 16, v63
	v_and_or_b32 v47, v44, s82, v47
	v_and_or_b32 v46, v45, s82, v46
	v_and_or_b32 v45, v61, s82, v66
	v_and_or_b32 v44, v60, s82, v65
	ds_bpermute_b32 v60, v138, v64
	v_mov_b64_e32 v[70:71], v[26:27]
	v_mfma_f32_16x16x32_bf16 v[40:43], v[48:51], v[44:47], v[40:43]
	v_sub_f32_e32 v48, v135, v149
	v_mul_f32_e32 v48, 0x3fb8aa3b, v48
	v_mov_b64_e32 v[74:75], v[22:23]
	s_waitcnt lgkmcnt(2)
	v_mfma_f32_16x16x32_bf16 v[36:39], v[52:55], v[44:47], v[36:39]
	v_exp_f32_e32 v52, v48
	ds_read2_b64 v[48:51], v141 offset0:128 offset1:132
	s_waitcnt lgkmcnt(1)
	v_add_f32_e32 v53, v64, v60
	v_mfma_f32_16x16x32_bf16 v[32:35], v[56:59], v[44:47], v[32:35]
	v_add_f32_e32 v52, v52, v53
	v_div_scale_f32 v53, s[0:1], v52, v52, 1.0
	v_rcp_f32_e32 v54, v53
	s_waitcnt lgkmcnt(0)
; __host__ __device__ __forceinline__ size_t blk_off(int r, int c, int C) { return ((size_t)(r >> 6) * (size_t)(C >> 6) + (size_t)(c >> 6)) * 4096 + (size_t)(r & 63) * 64 + (size_t)(c & 63); }
; __device__ __forceinline__ unsigned pk2(float lo, float hi) { return f2bf(lo) | (f2bf(hi) << 16); }
; __device__ __forceinline__ void att_unit(LAS unsigned char* lds, const bf16* PROJ, const float* COS, const float* SIN, const float* sinks, bf16* YA, int u) {
;     ...
;         const float inv = 1.0f / l;
; #pragma unroll
;         for (int dt = 0; dt < 4; ++dt) { v2u w; w.x = pk2(o[dt][0] * inv, o[dt][1] * inv); w.y = pk2(o[dt][2] * inv, o[dt][3] * inv);
;             *(v2u*)(YA + pg8::blk_off((int)t, hq * 64 + 16 * dt + 4 * g, BRW)) = w; }
;         qlo = nlo; qhi = nhi; qc0 = nc0; qc1 = nc1; qs0 = ns0; qs1 = ns1;
;     }
	v_mfma_f32_16x16x32_bf16 v[28:31], v[48:51], v[44:47], v[28:31]
	v_fma_f32 v44, -v53, v54, 1.0
	v_fmac_f32_e32 v54, v44, v54
	v_div_scale_f32 v44, vcc, 1.0, v52, 1.0
	v_mul_f32_e32 v45, v44, v54
	v_fma_f32 v46, -v53, v45, v44
	s_ashr_i32 s0, s50, 6
	v_fmac_f32_e32 v45, v46, v54
	s_mul_i32 s0, s0, 12
	v_fma_f32 v44, -v53, v45, v44
	s_add_i32 s0, s0, s70
	v_div_fmas_f32 v44, v44, v54, v45
	s_ashr_i32 s1, s0, 31
	v_div_fixup_f32 v44, v44, v52, 1.0
	s_lshl_b64 s[0:1], s[0:1], 13
	v_mov_b32_e32 v49, v42
	v_mov_b32_e32 v42, v41
	s_add_u32 s0, s60, s0
	v_mov_b32_e32 v48, v40
	v_pk_mul_f32 v[40:41], v[42:43], v[44:45] op_sel_hi:[1,0]
	s_addc_u32 s1, s61, s1
	v_pk_mul_f32 v[48:49], v[48:49], v[44:45] op_sel_hi:[1,0]
	v_and_b32_sdwa v43, v41, v216 dst_sel:DWORD dst_unused:UNUSED_PAD src0_sel:WORD_1 src1_sel:DWORD
	v_lshl_add_u64 v[46:47], s[0:1], 0, v[2:3]
	v_and_b32_sdwa v2, v49, v216 dst_sel:DWORD dst_unused:UNUSED_PAD src0_sel:WORD_1 src1_sel:DWORD
	v_and_b32_sdwa v45, v40, v216 dst_sel:DWORD dst_unused:UNUSED_PAD src0_sel:WORD_1 src1_sel:DWORD
	v_add3_u32 v41, v41, v43, s81
	v_and_b32_sdwa v42, v48, v216 dst_sel:DWORD dst_unused:UNUSED_PAD src0_sel:WORD_1 src1_sel:DWORD
	v_add3_u32 v2, v49, v2, s81
	v_add3_u32 v40, v40, v45, s81
	v_and_b32_e32 v41, 0xffff0000, v41
	v_add3_u32 v42, v48, v42, s81
	v_and_b32_e32 v40, 0xffff0000, v40
	v_or_b32_sdwa v41, v41, v2 dst_sel:DWORD dst_unused:UNUSED_PAD src0_sel:DWORD src1_sel:WORD_1
	v_lshlrev_b32_e32 v2, 1, v132
	v_or_b32_sdwa v40, v40, v42 dst_sel:DWORD dst_unused:UNUSED_PAD src0_sel:DWORD src1_sel:WORD_1
	v_lshl_add_u64 v[42:43], v[46:47], 0, v[2:3]
	global_store_dwordx2 v[42:43], v[40:41], off
	v_mov_b32_e32 v40, v36
	v_mov_b32_e32 v41, v38
	v_pk_mul_f32 v[40:41], v[40:41], v[44:45] op_sel_hi:[1,0]
	v_mov_b32_e32 v38, v37
	v_pk_mul_f32 v[36:37], v[38:39], v[44:45] op_sel_hi:[1,0]
	v_and_b32_sdwa v38, v40, v216 dst_sel:DWORD dst_unused:UNUSED_PAD src0_sel:WORD_1 src1_sel:DWORD
	v_add3_u32 v38, v40, v38, s81
	v_and_b32_sdwa v39, v37, v216 dst_sel:DWORD dst_unused:UNUSED_PAD src0_sel:WORD_1 src1_sel:DWORD
	v_and_b32_sdwa v40, v36, v216 dst_sel:DWORD dst_unused:UNUSED_PAD src0_sel:WORD_1 src1_sel:DWORD
	v_and_b32_sdwa v2, v41, v216 dst_sel:DWORD dst_unused:UNUSED_PAD src0_sel:WORD_1 src1_sel:DWORD
	v_add3_u32 v37, v37, v39, s81
	v_add3_u32 v36, v36, v40, s81
	v_add3_u32 v2, v41, v2, s81
	v_and_b32_e32 v37, 0xffff0000, v37
	v_and_b32_e32 v36, 0xffff0000, v36
	v_or_b32_sdwa v37, v37, v2 dst_sel:DWORD dst_unused:UNUSED_PAD src0_sel:DWORD src1_sel:WORD_1
	v_or_b32_sdwa v36, v36, v38 dst_sel:DWORD dst_unused:UNUSED_PAD src0_sel:DWORD src1_sel:WORD_1
	global_store_dwordx2 v[42:43], v[36:37], off offset:32
	v_mov_b32_e32 v36, v32
	v_mov_b32_e32 v37, v34
	v_pk_mul_f32 v[36:37], v[36:37], v[44:45] op_sel_hi:[1,0]
	v_mov_b32_e32 v34, v33
	v_pk_mul_f32 v[32:33], v[34:35], v[44:45] op_sel_hi:[1,0]
	v_and_b32_sdwa v34, v36, v216 dst_sel:DWORD dst_unused:UNUSED_PAD src0_sel:WORD_1 src1_sel:DWORD
	v_add3_u32 v34, v36, v34, s81
	v_and_b32_sdwa v35, v33, v216 dst_sel:DWORD dst_unused:UNUSED_PAD src0_sel:WORD_1 src1_sel:DWORD
	v_and_b32_sdwa v36, v32, v216 dst_sel:DWORD dst_unused:UNUSED_PAD src0_sel:WORD_1 src1_sel:DWORD
	v_and_b32_sdwa v2, v37, v216 dst_sel:DWORD dst_unused:UNUSED_PAD src0_sel:WORD_1 src1_sel:DWORD
	v_add3_u32 v33, v33, v35, s81
	v_add3_u32 v32, v32, v36, s81
	v_add3_u32 v2, v37, v2, s81
	v_and_b32_e32 v33, 0xffff0000, v33
	v_and_b32_e32 v32, 0xffff0000, v32
	v_or_b32_sdwa v33, v33, v2 dst_sel:DWORD dst_unused:UNUSED_PAD src0_sel:DWORD src1_sel:WORD_1
	v_or_b32_sdwa v32, v32, v34 dst_sel:DWORD dst_unused:UNUSED_PAD src0_sel:DWORD src1_sel:WORD_1
	global_store_dwordx2 v[42:43], v[32:33], off offset:64
	v_mov_b32_e32 v32, v28
	v_mov_b32_e32 v33, v30
	v_pk_mul_f32 v[32:33], v[32:33], v[44:45] op_sel_hi:[1,0]
	v_mov_b32_e32 v30, v29
	v_pk_mul_f32 v[28:29], v[30:31], v[44:45] op_sel_hi:[1,0]
	v_and_b32_sdwa v30, v32, v216 dst_sel:DWORD dst_unused:UNUSED_PAD src0_sel:WORD_1 src1_sel:DWORD
	v_add3_u32 v30, v32, v30, s81
	v_and_b32_sdwa v31, v29, v216 dst_sel:DWORD dst_unused:UNUSED_PAD src0_sel:WORD_1 src1_sel:DWORD
	v_and_b32_sdwa v32, v28, v216 dst_sel:DWORD dst_unused:UNUSED_PAD src0_sel:WORD_1 src1_sel:DWORD
	v_and_b32_sdwa v2, v33, v216 dst_sel:DWORD dst_unused:UNUSED_PAD src0_sel:WORD_1 src1_sel:DWORD
	v_add3_u32 v29, v29, v31, s81
	v_add3_u32 v28, v28, v32, s81
	v_add3_u32 v2, v33, v2, s81
	v_and_b32_e32 v29, 0xffff0000, v29
	v_and_b32_e32 v28, 0xffff0000, v28
	v_or_b32_sdwa v29, v29, v2 dst_sel:DWORD dst_unused:UNUSED_PAD src0_sel:DWORD src1_sel:WORD_1
	v_or_b32_sdwa v28, v28, v30 dst_sel:DWORD dst_unused:UNUSED_PAD src0_sel:DWORD src1_sel:WORD_1
	global_store_dwordx2 v[42:43], v[28:29], off offset:96
	s_add_i32 s45, s45, 16
	v_mov_b64_e32 v[38:39], v[18:19]
	v_mov_b64_e32 v[34:35], v[14:15]
	v_mov_b64_e32 v[54:55], v[18:19]
	v_mov_b64_e32 v[58:59], v[14:15]
	v_mov_b64_e32 v[46:47], v[10:11]
	v_mov_b64_e32 v[30:31], v[6:7]
	v_mov_b64_e32 v[50:51], v[26:27]
	v_mov_b64_e32 v[42:43], v[22:23]
	v_mov_b64_e32 v[62:63], v[10:11]
	v_mov_b64_e32 v[66:67], v[6:7]
	s_cmp_lg_u32 s45, 48
	v_mov_b64_e32 v[36:37], v[16:17]
	v_mov_b64_e32 v[32:33], v[12:13]
	v_mov_b64_e32 v[52:53], v[16:17]
	v_mov_b64_e32 v[56:57], v[12:13]
	v_mov_b64_e32 v[44:45], v[8:9]
	v_mov_b64_e32 v[28:29], v[4:5]
	v_mov_b64_e32 v[48:49], v[24:25]
	v_mov_b64_e32 v[40:41], v[20:21]
	v_mov_b64_e32 v[60:61], v[8:9]
	v_mov_b64_e32 v[64:65], v[4:5]
	v_mov_b64_e32 v[68:69], v[24:25]
	v_mov_b64_e32 v[72:73], v[20:21]
	s_cbranch_scc0 .LBB0_905

; __host__ __device__ __forceinline__ size_t blk_off(int r, int c, int C) { return ((size_t)(r >> 6) * (size_t)(C >> 6) + (size_t)(c >> 6)) * 4096 + (size_t)(r & 63) * 64 + (size_t)(c & 63); }
; __device__ __forceinline__ unsigned pk2(float lo, float hi) { return f2bf(lo) | (f2bf(hi) << 16); }
; __device__ __forceinline__ void att_unit(LAS unsigned char* lds, const bf16* PROJ, const float* COS, const float* SIN, const float* sinks, bf16* YA, int u) {
;     ...
;         const float inv = 1.0f / l;
; #pragma unroll
;         for (int dt = 0; dt < 4; ++dt) { v2u w; w.x = pk2(o[dt][0] * inv, o[dt][1] * inv); w.y = pk2(o[dt][2] * inv, o[dt][3] * inv);
;             *(v2u*)(YA + pg8::blk_off((int)t, hq * 64 + 16 * dt + 4 * g, BRW)) = w; }
;         qlo = nlo; qhi = nhi; qc0 = nc0; qc1 = nc1; qs0 = ns0; qs1 = ns1;
.LBB0_920:
	s_andn2_b64 vcc, exec, s[0:1]
	s_cbranch_vccnz .LBB0_917
	v_mov_b64_e32 v[20:21], v[72:73]
	v_mov_b64_e32 v[24:25], v[68:69]
	v_mov_b64_e32 v[4:5], v[64:65]
	v_mov_b64_e32 v[8:9], v[60:61]
	v_mov_b64_e32 v[12:13], v[56:57]
	v_mov_b64_e32 v[16:17], v[52:53]
	s_add_i32 s49, s2, 1
	v_mov_b64_e32 v[22:23], v[74:75]
	v_mov_b64_e32 v[26:27], v[70:71]
	v_mov_b64_e32 v[6:7], v[66:67]
	v_mov_b64_e32 v[10:11], v[62:63]
	v_mov_b64_e32 v[14:15], v[58:59]
	v_mov_b64_e32 v[18:19], v[54:55]
	s_branch .LBB0_917
